# GDN recurrence: four 2-byte output writes per sub-chunk packed into two 4-byte writes (DPP neighbour exchange + v_perm_b32); on top of the conv-sweep wait/barrier removal
# speedup vs baseline: 1.0024x; 1.0024x over previous
; __device__ __forceinline__ void phase_gdn2(Frame& F, bool ctx_out, bool dry = false) {
;     ...
;                 f32x4 U[4];
; #pragma unroll
;                 for (int I = 0; I < 4; ++I) {
;                     const hb8 fa = *(const LAS hb8*)(TUB + (I * 16 + l15) * GB + q4 * 8), fb = *(const LAS hb8*)(VT + (vb * 16 + l15) * GT + I * 16 + q4 * 8);
;                     U[I] = MFMA16(fa, fb, ((f32x4){0.f, 0.f, 0.f, 0.f}));
;                     const hb8 ga = *(const LAS hb8*)(KCT + (vb * 16 + l15) * GT + I * 16 + q4 * 8), gbv = *(const LAS hb8*)(TWB + (I * 16 + l15) * GB + q4 * 8);
;                     const f32x4 wt = MFMA16(ga, gbv, ((f32x4){0.f, 0.f, 0.f, 0.f}));
;                     *(LAS v2u*)(W + (I * 16 + l15) * GS + vb * 16 + q4 * 4) = (v2u){pk2(-wt.x, -wt.y), pk2(-wt.z, -wt.w)};
;                 }
;                 LDS_WAIT(); asm volatile("" ::: "memory");
;                 LDS_BARRIER();
; #pragma unroll
;                 for (int I = 0; I < 4; ++I) {
;                     f32x4 vn = U[I], oa = (f32x4){0.f, 0.f, 0.f, 0.f};
; #pragma unroll
;                     for (int ks = 0; ks < 4; ++ks) {
;                         const v4u sb4 = (v4u){pk2(S[2 * ks].x, S[2 * ks].y), pk2(S[2 * ks].z, S[2 * ks].w), pk2(S[2 * ks + 1].x, S[2 * ks + 1].y), pk2(S[2 * ks + 1].z, S[2 * ks + 1].w)};
;                         const hb8 fb = __builtin_bit_cast(hb8, sb4);
;                         const v2u w0 = *(const LAS v2u*)(W + (I * 16 + l15) * GS + ks * 32 + q4 * 4), w1 = *(const LAS v2u*)(W + (I * 16 + l15) * GS + ks * 32 + 16 + q4 * 4);
;                         const v2u q0 = *(const LAS v2u*)(QC + (I * 16 + l15) * GS + ks * 32 + q4 * 4), q1 = *(const LAS v2u*)(QC + (I * 16 + l15) * GS + ks * 32 + 16 + q4 * 4);
;                         const v4u fw4 = (v4u){w0.x, w0.y, w1.x, w1.y}, fq4 = (v4u){q0.x, q0.y, q1.x, q1.y};
;                         vn = MFMA16(__builtin_bit_cast(hb8, fw4), fb, vn); oa = MFMA16(__builtin_bit_cast(hb8, fq4), fb, oa); }
;                     const f32x4 ck = *(const LAS f32x4*)(s_ckd + I * 16 + q4 * 4), eg = *(const LAS f32x4*)(s_eG + I * 16 + q4 * 4), rqv = *(const LAS f32x4*)(s_rq + I * 16 + q4 * 4);
;                     const v4u vn4 = (v4u){pk2(vn.x, vn.y), pk2(vn.z, vn.w), 0u, 0u}, vp4 = (v4u){pk2(vn.x * ck.x, vn.y * ck.y), pk2(vn.z * ck.z, vn.w * ck.w), 0u, 0u};
;                     oa = oa * eg;
.Lgdn_drained:
	v_add3_u32 v88, s0, v0, v1
	v_add3_u32 v89, s47, v0, v1
	ds_read_b128 v[154:157], v88
	ds_read_b128 v[158:161], v3 offset:55296
	ds_read_b128 v[162:165], v3 offset:34816
	ds_read_b128 v[166:169], v89
	ds_read_b128 v[170:173], v88 offset:1280
	ds_read_b128 v[174:177], v3 offset:55328
	ds_read_b128 v[178:181], v3 offset:34848
	ds_read_b128 v[182:185], v89 offset:1280
	ds_read_b128 v[186:189], v88 offset:2560
	ds_read_b128 v[190:193], v3 offset:55360
	ds_read_b128 v[194:197], v3 offset:34880
	ds_read_b128 v[198:201], v89 offset:2560
	ds_read_b128 v[202:205], v88 offset:3840
	ds_read_b128 v[206:209], v3 offset:55392
	ds_read_b128 v[210:213], v3 offset:34912
	ds_read_b128 v[214:217], v89 offset:3840
	v_add_u32_e32 v108, 0, v139
	v_add_u32_e32 v107, s76, v140
	v_add_u32_e32 v101, s85, v139
	v_mul_u32_u24_e32 v84, 0x110, v137
	v_add3_u32 v92, s67, v139, v84
	v_mad_u32_u24 v103, v137, s10, v108
	v_or_b32_e32 v110, 16, v137
	v_mad_u32_u24 v104, v110, s10, v108
	v_or_b32_e32 v109, 32, v137
	v_or_b32_e32 v100, 48, v137
	s_add_i32 s56, s56, 1
	s_add_i32 s3, s3, 64
	s_add_i32 s96, s96, 1
	s_cmpk_eq_i32 s3, 0x900
	s_waitcnt lgkmcnt(14)
	v_mfma_f32_16x16x32_bf16 v[68:71], v[154:157], v[158:161], 0
	s_waitcnt lgkmcnt(12)
	v_mfma_f32_16x16x32_bf16 v[218:221], v[162:165], v[166:169], 0
	s_waitcnt lgkmcnt(10)
	v_mfma_f32_16x16x32_bf16 v[80:83], v[170:173], v[174:177], 0
	s_waitcnt lgkmcnt(8)
	v_mfma_f32_16x16x32_bf16 v[222:225], v[178:181], v[182:185], 0
	s_waitcnt lgkmcnt(6)
	v_mfma_f32_16x16x32_bf16 v[76:79], v[186:189], v[190:193], 0
	s_waitcnt lgkmcnt(4)
	v_mfma_f32_16x16x32_bf16 v[226:229], v[194:197], v[198:201], 0
	s_waitcnt lgkmcnt(2)
	v_mfma_f32_16x16x32_bf16 v[72:75], v[202:205], v[206:209], 0
	s_waitcnt lgkmcnt(0)
	v_mfma_f32_16x16x32_bf16 v[230:233], v[210:213], v[214:217], 0
	v_xor_b32_e32 v0, 0x80000000, v219
	v_xor_b32_e32 v1, 0x80000000, v218
	v_cvt_pk_bf16_f32 v0, v1, v0
	v_xor_b32_e32 v1, 0x80000000, v220
	v_xor_b32_e32 v84, 0x80000000, v221
	v_cvt_pk_bf16_f32 v1, v1, v84
	ds_write_b64 v92, v[0:1]
	v_xor_b32_e32 v0, 0x80000000, v223
	v_xor_b32_e32 v1, 0x80000000, v222
	v_cvt_pk_bf16_f32 v0, v1, v0
	v_xor_b32_e32 v1, 0x80000000, v224
	v_xor_b32_e32 v84, 0x80000000, v225
	v_cvt_pk_bf16_f32 v1, v1, v84
	ds_write_b64 v92, v[0:1] offset:4352
	v_xor_b32_e32 v0, 0x80000000, v227
	v_xor_b32_e32 v1, 0x80000000, v226
	v_cvt_pk_bf16_f32 v0, v1, v0
	v_xor_b32_e32 v1, 0x80000000, v228
	v_xor_b32_e32 v84, 0x80000000, v229
	v_cvt_pk_bf16_f32 v1, v1, v84
	ds_write_b64 v92, v[0:1] offset:8704
	v_xor_b32_e32 v0, 0x80000000, v231
	v_xor_b32_e32 v1, 0x80000000, v230
	v_cvt_pk_bf16_f32 v0, v1, v0
	v_xor_b32_e32 v1, 0x80000000, v232
	v_xor_b32_e32 v84, 0x80000000, v233
	v_cvt_pk_bf16_f32 v1, v1, v84
	ds_write_b64 v92, v[0:1] offset:13056
	v_add_u32_e32 v0, 0, v140
	s_waitcnt lgkmcnt(0)
	v_add_u32_e32 v106, 0x24a80, v0
	v_add_u32_e32 v102, 0x24b80, v0
	v_mul_u32_u24_e32 v0, 0x88, v137
	v_lshl_add_u32 v0, v0, 1, v108
	s_waitcnt lgkmcnt(0)
	s_barrier
	v_mov_b32_e32 v218, 0
	v_mov_b32_e32 v219, 0
	v_mov_b32_e32 v234, 0
	v_mov_b32_e32 v235, 0
	v_mov_b32_e32 v242, 0
	v_mov_b32_e32 v243, 0
	v_mov_b32_e32 v246, 0
	v_mov_b32_e32 v247, 0
	v_mov_b32_e32 v250, s76
	ds_read_b128 v[236:239], v250 offset:768
	ds_read_b64 v[154:155], v0
	ds_read_b64 v[156:157], v0 offset:32
	ds_read_b64 v[170:171], v0 offset:17408
	ds_read_b64 v[172:173], v0 offset:17440
	ds_read_b64 v[158:159], v0 offset:64
	ds_read_b64 v[160:161], v0 offset:96
	ds_read_b64 v[174:175], v0 offset:17472
	ds_read_b64 v[176:177], v0 offset:17504
	v_mad_u32_u24 v252, v137, s84, v101
	v_lshlrev_b32_e32 v92, 1, v137
	v_mul_u32_u24_e32 v93, 0x440, v138
	v_add3_u32 v253, s89, v92, v93
	v_and_b32_e32 v92, 1, v137
	v_mul_u32_u24_e32 v93, 0x10e, v92
	v_add_u32_e32 v93, v253, v93
	v_mul_u32_u24_e32 v92, 6, v92
	v_perm_b32 v92, v92, v92, 0
	v_xor_b32_e32 v92, 0x5040100, v92
	v_cvt_pk_bf16_f32 v186, v36, v37
	v_cvt_pk_bf16_f32 v187, v38, v39
	v_cvt_pk_bf16_f32 v188, v40, v41
	v_cvt_pk_bf16_f32 v189, v42, v43
	ds_read_b64 v[162:163], v0 offset:128
	ds_read_b64 v[164:165], v0 offset:160
	ds_read_b64 v[178:179], v0 offset:17536
	ds_read_b64 v[180:181], v0 offset:17568
	s_waitcnt lgkmcnt(8)
	v_mfma_f32_16x16x32_bf16 v[68:71], v[154:157], v[186:189], v[68:71]
	v_mfma_f32_16x16x32_bf16 v[84:87], v[170:173], v[186:189], 0
	v_cvt_pk_bf16_f32 v190, v44, v45
	v_cvt_pk_bf16_f32 v191, v46, v47
	v_cvt_pk_bf16_f32 v192, v48, v49
	v_cvt_pk_bf16_f32 v193, v50, v51
	ds_read_b64 v[166:167], v0 offset:192
	ds_read_b64 v[168:169], v0 offset:224
	ds_read_b64 v[182:183], v0 offset:17600
	ds_read_b64 v[184:185], v0 offset:17632
	s_waitcnt lgkmcnt(8)
	v_mfma_f32_16x16x32_bf16 v[68:71], v[158:161], v[190:193], v[68:71]
	v_mfma_f32_16x16x32_bf16 v[84:87], v[174:177], v[190:193], v[84:87]
	v_cvt_pk_bf16_f32 v194, v52, v53
	v_cvt_pk_bf16_f32 v195, v54, v55
	v_cvt_pk_bf16_f32 v196, v56, v57
	v_cvt_pk_bf16_f32 v197, v58, v59
	ds_read_b64 v[202:203], v103 offset:34816
	ds_read_b64 v[204:205], v104 offset:34816
	ds_read_b64 v[206:207], v104 offset:37120
	ds_read_b64 v[208:209], v104 offset:39424
	s_waitcnt lgkmcnt(8)
	v_mfma_f32_16x16x32_bf16 v[68:71], v[162:165], v[194:197], v[68:71]
	v_mfma_f32_16x16x32_bf16 v[84:87], v[178:181], v[194:197], v[84:87]
	v_cvt_pk_bf16_f32 v198, v60, v61
	v_cvt_pk_bf16_f32 v199, v62, v63
	v_cvt_pk_bf16_f32 v200, v64, v65
	v_cvt_pk_bf16_f32 v201, v66, v67
	ds_read_b64 v[210:211], v103 offset:44032
	ds_read_b64 v[212:213], v103 offset:46336
	ds_read_b64 v[214:215], v103 offset:48640
	ds_read_b64 v[216:217], v103 offset:50944
	s_waitcnt lgkmcnt(8)
; #define LAS __attribute__((address_space(3)))
; __device__ __forceinline__ void phase_gdn2(Frame& F, bool ctx_out, bool dry = false) {
;     ...
;                 for (int I = 0; I < 4; ++I) {
;                     f32x4 vn = U[I], oa = (f32x4){0.f, 0.f, 0.f, 0.f};
; #pragma unroll
;                     for (int ks = 0; ks < 4; ++ks) {
;                         const v4u sb4 = (v4u){pk2(S[2 * ks].x, S[2 * ks].y), pk2(S[2 * ks].z, S[2 * ks].w), pk2(S[2 * ks + 1].x, S[2 * ks + 1].y), pk2(S[2 * ks + 1].z, S[2 * ks + 1].w)};
;                         const hb8 fb = __builtin_bit_cast(hb8, sb4);
;                         const v2u w0 = *(const LAS v2u*)(W + (I * 16 + l15) * GS + ks * 32 + q4 * 4), w1 = *(const LAS v2u*)(W + (I * 16 + l15) * GS + ks * 32 + 16 + q4 * 4);
;                         const v2u q0 = *(const LAS v2u*)(QC + (I * 16 + l15) * GS + ks * 32 + q4 * 4), q1 = *(const LAS v2u*)(QC + (I * 16 + l15) * GS + ks * 32 + 16 + q4 * 4);
;                         const v4u fw4 = (v4u){w0.x, w0.y, w1.x, w1.y}, fq4 = (v4u){q0.x, q0.y, q1.x, q1.y};
;                         vn = MFMA16(__builtin_bit_cast(hb8, fw4), fb, vn); oa = MFMA16(__builtin_bit_cast(hb8, fq4), fb, oa); }
;                     const f32x4 ck = *(const LAS f32x4*)(s_ckd + I * 16 + q4 * 4), eg = *(const LAS f32x4*)(s_eG + I * 16 + q4 * 4), rqv = *(const LAS f32x4*)(s_rq + I * 16 + q4 * 4);
;                     const v4u vn4 = (v4u){pk2(vn.x, vn.y), pk2(vn.z, vn.w), 0u, 0u}, vp4 = (v4u){pk2(vn.x * ck.x, vn.y * ck.y), pk2(vn.z * ck.z, vn.w * ck.w), 0u, 0u};
;                     oa = oa * eg;
;                     { const v2u a0 = *(const LAS v2u*)(QKB + (I * 16 + l15) * GB + q4 * 4); const v4u fa4 = (v4u){a0.x, a0.y, 0u, 0u}; oa = MFMA16(__builtin_bit_cast(hb8, fa4), __builtin_bit_cast(hb8, vn4), oa); }
;                     oa = oa * rqv;
; #pragma unroll
;                     for (int i = 0; i < 4; ++i) O16[(I * 16 + q4 * 4 + i) * GS + vb * 16 + l15] = (bf16)f2bf(oa[i]);
;                     const float ege = s_eGend[I];
;                     const hb8 fbn = __builtin_bit_cast(hb8, vp4);
; #pragma unroll
;                     for (int kt = 0; kt < 8; ++kt) { const v2u a0 = *(const LAS v2u*)(KCT + (kt * 16 + l15) * GT + I * 16 + q4 * 4); const v4u fa4 = (v4u){a0.x, a0.y, 0u, 0u}; S[kt] = MFMA16(__builtin_bit_cast(hb8, fa4), fbn, S[kt] * ege); }
	v_mfma_f32_16x16x32_bf16 v[68:71], v[166:169], v[198:201], v[68:71]
	v_mfma_f32_16x16x32_bf16 v[84:87], v[182:185], v[198:201], v[84:87]
	ds_read_b128 v[220:223], v106
	ds_read_b128 v[224:227], v107 offset:512
	ds_read_b128 v[228:231], v102
	ds_read_b64 v[232:233], v252
	v_pk_mul_f32 v[36:37], v[36:37], v[236:237] op_sel_hi:[1,0]
	v_pk_mul_f32 v[38:39], v[38:39], v[236:237] op_sel_hi:[1,0]
	v_pk_mul_f32 v[40:41], v[40:41], v[236:237] op_sel_hi:[1,0]
	v_pk_mul_f32 v[42:43], v[42:43], v[236:237] op_sel_hi:[1,0]
	v_pk_mul_f32 v[44:45], v[44:45], v[236:237] op_sel_hi:[1,0]
	v_pk_mul_f32 v[46:47], v[46:47], v[236:237] op_sel_hi:[1,0]
	v_pk_mul_f32 v[48:49], v[48:49], v[236:237] op_sel_hi:[1,0]
	v_pk_mul_f32 v[50:51], v[50:51], v[236:237] op_sel_hi:[1,0]
	v_pk_mul_f32 v[52:53], v[52:53], v[236:237] op_sel_hi:[1,0]
	v_pk_mul_f32 v[54:55], v[54:55], v[236:237] op_sel_hi:[1,0]
	v_pk_mul_f32 v[56:57], v[56:57], v[236:237] op_sel_hi:[1,0]
	v_pk_mul_f32 v[58:59], v[58:59], v[236:237] op_sel_hi:[1,0]
	v_pk_mul_f32 v[60:61], v[60:61], v[236:237] op_sel_hi:[1,0]
	v_pk_mul_f32 v[62:63], v[62:63], v[236:237] op_sel_hi:[1,0]
	v_pk_mul_f32 v[64:65], v[64:65], v[236:237] op_sel_hi:[1,0]
	v_pk_mul_f32 v[66:67], v[66:67], v[236:237] op_sel_hi:[1,0]
	s_waitcnt lgkmcnt(2)
	v_cvt_pk_bf16_f32 v240, v68, v69
	v_cvt_pk_bf16_f32 v241, v70, v71
	v_pk_mul_f32 v[88:89], v[68:69], v[220:221]
	v_pk_mul_f32 v[90:91], v[70:71], v[222:223]
	v_cvt_pk_bf16_f32 v244, v88, v89
	v_cvt_pk_bf16_f32 v245, v90, v91
	v_pk_mul_f32 v[84:85], v[84:85], v[224:225]
	v_pk_mul_f32 v[86:87], v[86:87], v[226:227]
	s_waitcnt lgkmcnt(0)
	v_mfma_f32_16x16x32_bf16 v[36:39], v[202:205], v[244:247], v[36:39]
	v_mfma_f32_16x16x32_bf16 v[40:43], v[204:207], v[244:247], v[40:43]
	v_mfma_f32_16x16x32_bf16 v[84:87], v[232:235], v[240:243], v[84:87]
	v_add_u32_e32 v250, 4352, v0
	v_mfma_f32_16x16x32_bf16 v[44:47], v[206:209], v[244:247], v[44:47]
	v_mfma_f32_16x16x32_bf16 v[48:51], v[208:211], v[244:247], v[48:51]
	v_mfma_f32_16x16x32_bf16 v[52:55], v[210:213], v[244:247], v[52:55]
	v_mfma_f32_16x16x32_bf16 v[56:59], v[212:215], v[244:247], v[56:59]
	v_mfma_f32_16x16x32_bf16 v[60:63], v[214:217], v[244:247], v[60:63]
	v_mfma_f32_16x16x32_bf16 v[64:67], v[216:219], v[244:247], v[64:67]
	ds_read_b64 v[154:155], v250
	ds_read_b64 v[156:157], v250 offset:32
	ds_read_b64 v[170:171], v250 offset:17408
	ds_read_b64 v[172:173], v250 offset:17440
	ds_read_b64 v[158:159], v250 offset:64
	ds_read_b64 v[160:161], v250 offset:96
	ds_read_b64 v[174:175], v250 offset:17472
	ds_read_b64 v[176:177], v250 offset:17504
	v_pk_mul_f32 v[84:85], v[84:85], v[228:229]
	v_pk_mul_f32 v[86:87], v[86:87], v[230:231]
	v_cvt_pk_bf16_f32 v88, v84, v85
	v_cvt_pk_bf16_f32 v90, v86, v87
	s_nop 1
	v_mov_b32_dpp v89, v88 quad_perm:[1,0,3,2] row_mask:0xf bank_mask:0xf
	v_mov_b32_dpp v91, v90 quad_perm:[1,0,3,2] row_mask:0xf bank_mask:0xf
	v_perm_b32 v88, v89, v88, v92
	v_perm_b32 v90, v91, v90, v92
	ds_write_b32 v93, v88
	ds_write_b32 v93, v90 offset:544
	v_cvt_pk_bf16_f32 v186, v36, v37
	v_cvt_pk_bf16_f32 v187, v38, v39
	v_cvt_pk_bf16_f32 v188, v40, v41
	v_cvt_pk_bf16_f32 v189, v42, v43
	s_waitcnt lgkmcnt(8)
	ds_read_b64 v[162:163], v250 offset:128
	ds_read_b64 v[164:165], v250 offset:160
	ds_read_b64 v[178:179], v250 offset:17536
	ds_read_b64 v[180:181], v250 offset:17568
	s_waitcnt lgkmcnt(8)
	v_mfma_f32_16x16x32_bf16 v[80:83], v[154:157], v[186:189], v[80:83]
	v_mfma_f32_16x16x32_bf16 v[84:87], v[170:173], v[186:189], 0
	v_cvt_pk_bf16_f32 v190, v44, v45
	v_cvt_pk_bf16_f32 v191, v46, v47
	v_cvt_pk_bf16_f32 v192, v48, v49
	v_cvt_pk_bf16_f32 v193, v50, v51
	ds_read_b64 v[166:167], v250 offset:192
	ds_read_b64 v[168:169], v250 offset:224
	ds_read_b64 v[182:183], v250 offset:17600
	ds_read_b64 v[184:185], v250 offset:17632
	s_waitcnt lgkmcnt(8)
	v_mfma_f32_16x16x32_bf16 v[80:83], v[158:161], v[190:193], v[80:83]
	v_mfma_f32_16x16x32_bf16 v[84:87], v[174:177], v[190:193], v[84:87]
	v_cvt_pk_bf16_f32 v194, v52, v53
	v_cvt_pk_bf16_f32 v195, v54, v55
	v_cvt_pk_bf16_f32 v196, v56, v57
	v_cvt_pk_bf16_f32 v197, v58, v59
	ds_read_b64 v[202:203], v103 offset:34848
	ds_read_b64 v[204:205], v104 offset:34848
	ds_read_b64 v[206:207], v104 offset:37152
	ds_read_b64 v[208:209], v104 offset:39456
	s_waitcnt lgkmcnt(8)
	v_mfma_f32_16x16x32_bf16 v[80:83], v[162:165], v[194:197], v[80:83]
	v_mfma_f32_16x16x32_bf16 v[84:87], v[178:181], v[194:197], v[84:87]
	v_cvt_pk_bf16_f32 v198, v60, v61
	v_cvt_pk_bf16_f32 v199, v62, v63
	v_cvt_pk_bf16_f32 v200, v64, v65
	v_cvt_pk_bf16_f32 v201, v66, v67
	ds_read_b64 v[210:211], v103 offset:44064
	ds_read_b64 v[212:213], v103 offset:46368
	ds_read_b64 v[214:215], v103 offset:48672
	ds_read_b64 v[216:217], v103 offset:50976
	s_waitcnt lgkmcnt(8)
	v_mfma_f32_16x16x32_bf16 v[80:83], v[166:169], v[198:201], v[80:83]
	v_mfma_f32_16x16x32_bf16 v[84:87], v[182:185], v[198:201], v[84:87]
	ds_read_b128 v[220:223], v106 offset:64
	ds_read_b128 v[224:227], v107 offset:576
	ds_read_b128 v[228:231], v102 offset:64
	ds_read_b64 v[232:233], v252 offset:1280
	v_pk_mul_f32 v[36:37], v[36:37], v[236:237] op_sel:[0,1]
	v_pk_mul_f32 v[38:39], v[38:39], v[236:237] op_sel:[0,1]
	v_pk_mul_f32 v[40:41], v[40:41], v[236:237] op_sel:[0,1]
	v_pk_mul_f32 v[42:43], v[42:43], v[236:237] op_sel:[0,1]
	v_pk_mul_f32 v[44:45], v[44:45], v[236:237] op_sel:[0,1]
	v_pk_mul_f32 v[46:47], v[46:47], v[236:237] op_sel:[0,1]
	v_pk_mul_f32 v[48:49], v[48:49], v[236:237] op_sel:[0,1]
	v_pk_mul_f32 v[50:51], v[50:51], v[236:237] op_sel:[0,1]
	v_pk_mul_f32 v[52:53], v[52:53], v[236:237] op_sel:[0,1]
	v_pk_mul_f32 v[54:55], v[54:55], v[236:237] op_sel:[0,1]
	v_pk_mul_f32 v[56:57], v[56:57], v[236:237] op_sel:[0,1]
	v_pk_mul_f32 v[58:59], v[58:59], v[236:237] op_sel:[0,1]
	v_pk_mul_f32 v[60:61], v[60:61], v[236:237] op_sel:[0,1]
	v_pk_mul_f32 v[62:63], v[62:63], v[236:237] op_sel:[0,1]
	v_pk_mul_f32 v[64:65], v[64:65], v[236:237] op_sel:[0,1]
	v_pk_mul_f32 v[66:67], v[66:67], v[236:237] op_sel:[0,1]
	s_waitcnt lgkmcnt(2)
; #define LAS __attribute__((address_space(3)))
; __device__ __forceinline__ void phase_gdn2(Frame& F, bool ctx_out, bool dry = false) {
;     ...
;                 for (int I = 0; I < 4; ++I) {
;                     f32x4 vn = U[I], oa = (f32x4){0.f, 0.f, 0.f, 0.f};
; #pragma unroll
;                     for (int ks = 0; ks < 4; ++ks) {
;                         const v4u sb4 = (v4u){pk2(S[2 * ks].x, S[2 * ks].y), pk2(S[2 * ks].z, S[2 * ks].w), pk2(S[2 * ks + 1].x, S[2 * ks + 1].y), pk2(S[2 * ks + 1].z, S[2 * ks + 1].w)};
;                         const hb8 fb = __builtin_bit_cast(hb8, sb4);
;                         const v2u w0 = *(const LAS v2u*)(W + (I * 16 + l15) * GS + ks * 32 + q4 * 4), w1 = *(const LAS v2u*)(W + (I * 16 + l15) * GS + ks * 32 + 16 + q4 * 4);
;                         const v2u q0 = *(const LAS v2u*)(QC + (I * 16 + l15) * GS + ks * 32 + q4 * 4), q1 = *(const LAS v2u*)(QC + (I * 16 + l15) * GS + ks * 32 + 16 + q4 * 4);
;                         const v4u fw4 = (v4u){w0.x, w0.y, w1.x, w1.y}, fq4 = (v4u){q0.x, q0.y, q1.x, q1.y};
;                         vn = MFMA16(__builtin_bit_cast(hb8, fw4), fb, vn); oa = MFMA16(__builtin_bit_cast(hb8, fq4), fb, oa); }
;                     const f32x4 ck = *(const LAS f32x4*)(s_ckd + I * 16 + q4 * 4), eg = *(const LAS f32x4*)(s_eG + I * 16 + q4 * 4), rqv = *(const LAS f32x4*)(s_rq + I * 16 + q4 * 4);
;                     const v4u vn4 = (v4u){pk2(vn.x, vn.y), pk2(vn.z, vn.w), 0u, 0u}, vp4 = (v4u){pk2(vn.x * ck.x, vn.y * ck.y), pk2(vn.z * ck.z, vn.w * ck.w), 0u, 0u};
;                     oa = oa * eg;
;                     { const v2u a0 = *(const LAS v2u*)(QKB + (I * 16 + l15) * GB + q4 * 4); const v4u fa4 = (v4u){a0.x, a0.y, 0u, 0u}; oa = MFMA16(__builtin_bit_cast(hb8, fa4), __builtin_bit_cast(hb8, vn4), oa); }
;                     oa = oa * rqv;
; #pragma unroll
;                     for (int i = 0; i < 4; ++i) O16[(I * 16 + q4 * 4 + i) * GS + vb * 16 + l15] = (bf16)f2bf(oa[i]);
;                     const float ege = s_eGend[I];
;                     const hb8 fbn = __builtin_bit_cast(hb8, vp4);
; #pragma unroll
;                     for (int kt = 0; kt < 8; ++kt) { const v2u a0 = *(const LAS v2u*)(KCT + (kt * 16 + l15) * GT + I * 16 + q4 * 4); const v4u fa4 = (v4u){a0.x, a0.y, 0u, 0u}; S[kt] = MFMA16(__builtin_bit_cast(hb8, fa4), fbn, S[kt] * ege); }
	v_cvt_pk_bf16_f32 v240, v80, v81
	v_cvt_pk_bf16_f32 v241, v82, v83
	v_pk_mul_f32 v[88:89], v[80:81], v[220:221]
	v_pk_mul_f32 v[90:91], v[82:83], v[222:223]
	v_cvt_pk_bf16_f32 v244, v88, v89
	v_cvt_pk_bf16_f32 v245, v90, v91
	v_pk_mul_f32 v[84:85], v[84:85], v[224:225]
	v_pk_mul_f32 v[86:87], v[86:87], v[226:227]
	s_waitcnt lgkmcnt(0)
	v_mfma_f32_16x16x32_bf16 v[36:39], v[202:205], v[244:247], v[36:39]
	v_mfma_f32_16x16x32_bf16 v[40:43], v[204:207], v[244:247], v[40:43]
	v_mfma_f32_16x16x32_bf16 v[84:87], v[232:235], v[240:243], v[84:87]
	v_add_u32_e32 v250, 8704, v0
	v_mfma_f32_16x16x32_bf16 v[44:47], v[206:209], v[244:247], v[44:47]
	v_mfma_f32_16x16x32_bf16 v[48:51], v[208:211], v[244:247], v[48:51]
	v_mfma_f32_16x16x32_bf16 v[52:55], v[210:213], v[244:247], v[52:55]
	v_mfma_f32_16x16x32_bf16 v[56:59], v[212:215], v[244:247], v[56:59]
	v_mfma_f32_16x16x32_bf16 v[60:63], v[214:217], v[244:247], v[60:63]
	v_mfma_f32_16x16x32_bf16 v[64:67], v[216:219], v[244:247], v[64:67]
	ds_read_b64 v[154:155], v250
	ds_read_b64 v[156:157], v250 offset:32
	ds_read_b64 v[170:171], v250 offset:17408
	ds_read_b64 v[172:173], v250 offset:17440
	ds_read_b64 v[158:159], v250 offset:64
	ds_read_b64 v[160:161], v250 offset:96
	ds_read_b64 v[174:175], v250 offset:17472
	ds_read_b64 v[176:177], v250 offset:17504
	v_pk_mul_f32 v[84:85], v[84:85], v[228:229]
	v_pk_mul_f32 v[86:87], v[86:87], v[230:231]
	v_cvt_pk_bf16_f32 v88, v84, v85
	v_cvt_pk_bf16_f32 v90, v86, v87
	s_nop 1
	v_mov_b32_dpp v89, v88 quad_perm:[1,0,3,2] row_mask:0xf bank_mask:0xf
	v_mov_b32_dpp v91, v90 quad_perm:[1,0,3,2] row_mask:0xf bank_mask:0xf
	v_perm_b32 v88, v89, v88, v92
	v_perm_b32 v90, v91, v90, v92
	ds_write_b32 v93, v88 offset:4352
	ds_write_b32 v93, v90 offset:4896
	v_cvt_pk_bf16_f32 v186, v36, v37
	v_cvt_pk_bf16_f32 v187, v38, v39
	v_cvt_pk_bf16_f32 v188, v40, v41
	v_cvt_pk_bf16_f32 v189, v42, v43
	s_waitcnt lgkmcnt(8)
	ds_read_b64 v[162:163], v250 offset:128
	ds_read_b64 v[164:165], v250 offset:160
	ds_read_b64 v[178:179], v250 offset:17536
	ds_read_b64 v[180:181], v250 offset:17568
	s_waitcnt lgkmcnt(8)
	v_mfma_f32_16x16x32_bf16 v[76:79], v[154:157], v[186:189], v[76:79]
	v_mfma_f32_16x16x32_bf16 v[84:87], v[170:173], v[186:189], 0
	v_cvt_pk_bf16_f32 v190, v44, v45
	v_cvt_pk_bf16_f32 v191, v46, v47
	v_cvt_pk_bf16_f32 v192, v48, v49
	v_cvt_pk_bf16_f32 v193, v50, v51
	ds_read_b64 v[166:167], v250 offset:192
	ds_read_b64 v[168:169], v250 offset:224
	ds_read_b64 v[182:183], v250 offset:17600
	ds_read_b64 v[184:185], v250 offset:17632
	s_waitcnt lgkmcnt(8)
	v_mfma_f32_16x16x32_bf16 v[76:79], v[158:161], v[190:193], v[76:79]
	v_mfma_f32_16x16x32_bf16 v[84:87], v[174:177], v[190:193], v[84:87]
	v_cvt_pk_bf16_f32 v194, v52, v53
	v_cvt_pk_bf16_f32 v195, v54, v55
	v_cvt_pk_bf16_f32 v196, v56, v57
	v_cvt_pk_bf16_f32 v197, v58, v59
	ds_read_b64 v[202:203], v103 offset:34880
	ds_read_b64 v[204:205], v104 offset:34880
	ds_read_b64 v[206:207], v104 offset:37184
	ds_read_b64 v[208:209], v104 offset:39488
	s_waitcnt lgkmcnt(8)
	v_mfma_f32_16x16x32_bf16 v[76:79], v[162:165], v[194:197], v[76:79]
	v_mfma_f32_16x16x32_bf16 v[84:87], v[178:181], v[194:197], v[84:87]
	v_cvt_pk_bf16_f32 v198, v60, v61
	v_cvt_pk_bf16_f32 v199, v62, v63
	v_cvt_pk_bf16_f32 v200, v64, v65
	v_cvt_pk_bf16_f32 v201, v66, v67
	ds_read_b64 v[210:211], v103 offset:44096
	ds_read_b64 v[212:213], v103 offset:46400
	ds_read_b64 v[214:215], v103 offset:48704
	ds_read_b64 v[216:217], v103 offset:51008
	s_waitcnt lgkmcnt(8)
	v_mfma_f32_16x16x32_bf16 v[76:79], v[166:169], v[198:201], v[76:79]
	v_mfma_f32_16x16x32_bf16 v[84:87], v[182:185], v[198:201], v[84:87]
	ds_read_b128 v[220:223], v106 offset:128
	ds_read_b128 v[224:227], v107 offset:640
	ds_read_b128 v[228:231], v102 offset:128
	ds_read_b64 v[232:233], v252 offset:2560
	v_pk_mul_f32 v[36:37], v[36:37], v[238:239] op_sel_hi:[1,0]
	v_pk_mul_f32 v[38:39], v[38:39], v[238:239] op_sel_hi:[1,0]
	v_pk_mul_f32 v[40:41], v[40:41], v[238:239] op_sel_hi:[1,0]
	v_pk_mul_f32 v[42:43], v[42:43], v[238:239] op_sel_hi:[1,0]
	v_pk_mul_f32 v[44:45], v[44:45], v[238:239] op_sel_hi:[1,0]
	v_pk_mul_f32 v[46:47], v[46:47], v[238:239] op_sel_hi:[1,0]
	v_pk_mul_f32 v[48:49], v[48:49], v[238:239] op_sel_hi:[1,0]
	v_pk_mul_f32 v[50:51], v[50:51], v[238:239] op_sel_hi:[1,0]
	v_pk_mul_f32 v[52:53], v[52:53], v[238:239] op_sel_hi:[1,0]
	v_pk_mul_f32 v[54:55], v[54:55], v[238:239] op_sel_hi:[1,0]
	v_pk_mul_f32 v[56:57], v[56:57], v[238:239] op_sel_hi:[1,0]
	v_pk_mul_f32 v[58:59], v[58:59], v[238:239] op_sel_hi:[1,0]
	v_pk_mul_f32 v[60:61], v[60:61], v[238:239] op_sel_hi:[1,0]
	v_pk_mul_f32 v[62:63], v[62:63], v[238:239] op_sel_hi:[1,0]
	v_pk_mul_f32 v[64:65], v[64:65], v[238:239] op_sel_hi:[1,0]
	v_pk_mul_f32 v[66:67], v[66:67], v[238:239] op_sel_hi:[1,0]
	s_waitcnt lgkmcnt(2)
	v_cvt_pk_bf16_f32 v240, v76, v77
	v_cvt_pk_bf16_f32 v241, v78, v79
	v_pk_mul_f32 v[88:89], v[76:77], v[220:221]
	v_pk_mul_f32 v[90:91], v[78:79], v[222:223]
	v_cvt_pk_bf16_f32 v244, v88, v89
	v_cvt_pk_bf16_f32 v245, v90, v91
	v_pk_mul_f32 v[84:85], v[84:85], v[224:225]
	v_pk_mul_f32 v[86:87], v[86:87], v[226:227]
	s_waitcnt lgkmcnt(0)
; __device__ __forceinline__ void phase_gdn2(Frame& F, bool ctx_out, bool dry = false) {
;     ...
;                 for (int I = 0; I < 4; ++I) {
;                     f32x4 vn = U[I], oa = (f32x4){0.f, 0.f, 0.f, 0.f};
; #pragma unroll
;                     for (int ks = 0; ks < 4; ++ks) {
;                         const v4u sb4 = (v4u){pk2(S[2 * ks].x, S[2 * ks].y), pk2(S[2 * ks].z, S[2 * ks].w), pk2(S[2 * ks + 1].x, S[2 * ks + 1].y), pk2(S[2 * ks + 1].z, S[2 * ks + 1].w)};
;                         const hb8 fb = __builtin_bit_cast(hb8, sb4);
;                         const v2u w0 = *(const LAS v2u*)(W + (I * 16 + l15) * GS + ks * 32 + q4 * 4), w1 = *(const LAS v2u*)(W + (I * 16 + l15) * GS + ks * 32 + 16 + q4 * 4);
;                         const v2u q0 = *(const LAS v2u*)(QC + (I * 16 + l15) * GS + ks * 32 + q4 * 4), q1 = *(const LAS v2u*)(QC + (I * 16 + l15) * GS + ks * 32 + 16 + q4 * 4);
;                         const v4u fw4 = (v4u){w0.x, w0.y, w1.x, w1.y}, fq4 = (v4u){q0.x, q0.y, q1.x, q1.y};
;                         vn = MFMA16(__builtin_bit_cast(hb8, fw4), fb, vn); oa = MFMA16(__builtin_bit_cast(hb8, fq4), fb, oa); }
;                     const f32x4 ck = *(const LAS f32x4*)(s_ckd + I * 16 + q4 * 4), eg = *(const LAS f32x4*)(s_eG + I * 16 + q4 * 4), rqv = *(const LAS f32x4*)(s_rq + I * 16 + q4 * 4);
;                     const v4u vn4 = (v4u){pk2(vn.x, vn.y), pk2(vn.z, vn.w), 0u, 0u}, vp4 = (v4u){pk2(vn.x * ck.x, vn.y * ck.y), pk2(vn.z * ck.z, vn.w * ck.w), 0u, 0u};
;                     oa = oa * eg;
;                     { const v2u a0 = *(const LAS v2u*)(QKB + (I * 16 + l15) * GB + q4 * 4); const v4u fa4 = (v4u){a0.x, a0.y, 0u, 0u}; oa = MFMA16(__builtin_bit_cast(hb8, fa4), __builtin_bit_cast(hb8, vn4), oa); }
;                     oa = oa * rqv;
; #pragma unroll
;                     for (int i = 0; i < 4; ++i) O16[(I * 16 + q4 * 4 + i) * GS + vb * 16 + l15] = (bf16)f2bf(oa[i]);
;                     const float ege = s_eGend[I];
;                     const hb8 fbn = __builtin_bit_cast(hb8, vp4);
; #pragma unroll
;                     for (int kt = 0; kt < 8; ++kt) { const v2u a0 = *(const LAS v2u*)(KCT + (kt * 16 + l15) * GT + I * 16 + q4 * 4); const v4u fa4 = (v4u){a0.x, a0.y, 0u, 0u}; S[kt] = MFMA16(__builtin_bit_cast(hb8, fa4), fbn, S[kt] * ege); }
;                 }
;                 LDS_BARRIER();
	v_mfma_f32_16x16x32_bf16 v[36:39], v[202:205], v[244:247], v[36:39]
	v_mfma_f32_16x16x32_bf16 v[40:43], v[204:207], v[244:247], v[40:43]
	v_mfma_f32_16x16x32_bf16 v[84:87], v[232:235], v[240:243], v[84:87]
	v_add_u32_e32 v250, 13056, v0
	v_mfma_f32_16x16x32_bf16 v[44:47], v[206:209], v[244:247], v[44:47]
	v_mfma_f32_16x16x32_bf16 v[48:51], v[208:211], v[244:247], v[48:51]
	v_mfma_f32_16x16x32_bf16 v[52:55], v[210:213], v[244:247], v[52:55]
	v_mfma_f32_16x16x32_bf16 v[56:59], v[212:215], v[244:247], v[56:59]
	v_mfma_f32_16x16x32_bf16 v[60:63], v[214:217], v[244:247], v[60:63]
	v_mfma_f32_16x16x32_bf16 v[64:67], v[216:219], v[244:247], v[64:67]
	ds_read_b64 v[154:155], v250
	ds_read_b64 v[156:157], v250 offset:32
	ds_read_b64 v[170:171], v250 offset:17408
	ds_read_b64 v[172:173], v250 offset:17440
	ds_read_b64 v[158:159], v250 offset:64
	ds_read_b64 v[160:161], v250 offset:96
	ds_read_b64 v[174:175], v250 offset:17472
	ds_read_b64 v[176:177], v250 offset:17504
	v_pk_mul_f32 v[84:85], v[84:85], v[228:229]
	v_pk_mul_f32 v[86:87], v[86:87], v[230:231]
	v_cvt_pk_bf16_f32 v88, v84, v85
	v_cvt_pk_bf16_f32 v90, v86, v87
	s_nop 1
	v_mov_b32_dpp v89, v88 quad_perm:[1,0,3,2] row_mask:0xf bank_mask:0xf
	v_mov_b32_dpp v91, v90 quad_perm:[1,0,3,2] row_mask:0xf bank_mask:0xf
	v_perm_b32 v88, v89, v88, v92
	v_perm_b32 v90, v91, v90, v92
	ds_write_b32 v93, v88 offset:8704
	ds_write_b32 v93, v90 offset:9248
	v_cvt_pk_bf16_f32 v186, v36, v37
	v_cvt_pk_bf16_f32 v187, v38, v39
	v_cvt_pk_bf16_f32 v188, v40, v41
	v_cvt_pk_bf16_f32 v189, v42, v43
	s_waitcnt lgkmcnt(8)
	ds_read_b64 v[162:163], v250 offset:128
	ds_read_b64 v[164:165], v250 offset:160
	ds_read_b64 v[178:179], v250 offset:17536
	ds_read_b64 v[180:181], v250 offset:17568
	s_waitcnt lgkmcnt(8)
	v_mfma_f32_16x16x32_bf16 v[72:75], v[154:157], v[186:189], v[72:75]
	v_mfma_f32_16x16x32_bf16 v[84:87], v[170:173], v[186:189], 0
	v_cvt_pk_bf16_f32 v190, v44, v45
	v_cvt_pk_bf16_f32 v191, v46, v47
	v_cvt_pk_bf16_f32 v192, v48, v49
	v_cvt_pk_bf16_f32 v193, v50, v51
	ds_read_b64 v[166:167], v250 offset:192
	ds_read_b64 v[168:169], v250 offset:224
	ds_read_b64 v[182:183], v250 offset:17600
	ds_read_b64 v[184:185], v250 offset:17632
	s_waitcnt lgkmcnt(8)
	v_mfma_f32_16x16x32_bf16 v[72:75], v[158:161], v[190:193], v[72:75]
	v_mfma_f32_16x16x32_bf16 v[84:87], v[174:177], v[190:193], v[84:87]
	v_cvt_pk_bf16_f32 v194, v52, v53
	v_cvt_pk_bf16_f32 v195, v54, v55
	v_cvt_pk_bf16_f32 v196, v56, v57
	v_cvt_pk_bf16_f32 v197, v58, v59
	ds_read_b64 v[202:203], v103 offset:34912
	ds_read_b64 v[204:205], v104 offset:34912
	ds_read_b64 v[206:207], v104 offset:37216
	ds_read_b64 v[208:209], v104 offset:39520
	s_waitcnt lgkmcnt(8)
	v_mfma_f32_16x16x32_bf16 v[72:75], v[162:165], v[194:197], v[72:75]
	v_mfma_f32_16x16x32_bf16 v[84:87], v[178:181], v[194:197], v[84:87]
	v_cvt_pk_bf16_f32 v198, v60, v61
	v_cvt_pk_bf16_f32 v199, v62, v63
	v_cvt_pk_bf16_f32 v200, v64, v65
	v_cvt_pk_bf16_f32 v201, v66, v67
	ds_read_b64 v[210:211], v103 offset:44128
	ds_read_b64 v[212:213], v103 offset:46432
	ds_read_b64 v[214:215], v103 offset:48736
	ds_read_b64 v[216:217], v103 offset:51040
	s_waitcnt lgkmcnt(8)
	v_mfma_f32_16x16x32_bf16 v[72:75], v[166:169], v[198:201], v[72:75]
	v_mfma_f32_16x16x32_bf16 v[84:87], v[182:185], v[198:201], v[84:87]
	ds_read_b128 v[220:223], v106 offset:192
	ds_read_b128 v[224:227], v107 offset:704
	ds_read_b128 v[228:231], v102 offset:192
	ds_read_b64 v[232:233], v252 offset:3840
	v_pk_mul_f32 v[36:37], v[36:37], v[238:239] op_sel:[0,1]
	v_pk_mul_f32 v[38:39], v[38:39], v[238:239] op_sel:[0,1]
	v_pk_mul_f32 v[40:41], v[40:41], v[238:239] op_sel:[0,1]
	v_pk_mul_f32 v[42:43], v[42:43], v[238:239] op_sel:[0,1]
	v_pk_mul_f32 v[44:45], v[44:45], v[238:239] op_sel:[0,1]
	v_pk_mul_f32 v[46:47], v[46:47], v[238:239] op_sel:[0,1]
	v_pk_mul_f32 v[48:49], v[48:49], v[238:239] op_sel:[0,1]
	v_pk_mul_f32 v[50:51], v[50:51], v[238:239] op_sel:[0,1]
	v_pk_mul_f32 v[52:53], v[52:53], v[238:239] op_sel:[0,1]
	v_pk_mul_f32 v[54:55], v[54:55], v[238:239] op_sel:[0,1]
	v_pk_mul_f32 v[56:57], v[56:57], v[238:239] op_sel:[0,1]
	v_pk_mul_f32 v[58:59], v[58:59], v[238:239] op_sel:[0,1]
	v_pk_mul_f32 v[60:61], v[60:61], v[238:239] op_sel:[0,1]
	v_pk_mul_f32 v[62:63], v[62:63], v[238:239] op_sel:[0,1]
	v_pk_mul_f32 v[64:65], v[64:65], v[238:239] op_sel:[0,1]
	v_pk_mul_f32 v[66:67], v[66:67], v[238:239] op_sel:[0,1]
	s_waitcnt lgkmcnt(2)
	v_cvt_pk_bf16_f32 v240, v72, v73
	v_cvt_pk_bf16_f32 v241, v74, v75
	v_pk_mul_f32 v[88:89], v[72:73], v[220:221]
	v_pk_mul_f32 v[90:91], v[74:75], v[222:223]
	v_cvt_pk_bf16_f32 v244, v88, v89
	v_cvt_pk_bf16_f32 v245, v90, v91
	v_pk_mul_f32 v[84:85], v[84:85], v[224:225]
	v_pk_mul_f32 v[86:87], v[86:87], v[226:227]
	s_waitcnt lgkmcnt(0)
	v_mfma_f32_16x16x32_bf16 v[36:39], v[202:205], v[244:247], v[36:39]
	v_mfma_f32_16x16x32_bf16 v[40:43], v[204:207], v[244:247], v[40:43]
	v_mfma_f32_16x16x32_bf16 v[84:87], v[232:235], v[240:243], v[84:87]
	v_mfma_f32_16x16x32_bf16 v[44:47], v[206:209], v[244:247], v[44:47]
	v_mfma_f32_16x16x32_bf16 v[48:51], v[208:211], v[244:247], v[48:51]
	v_mfma_f32_16x16x32_bf16 v[52:55], v[210:213], v[244:247], v[52:55]
	v_mfma_f32_16x16x32_bf16 v[56:59], v[212:215], v[244:247], v[56:59]
	v_mfma_f32_16x16x32_bf16 v[60:63], v[214:217], v[244:247], v[60:63]
	v_mfma_f32_16x16x32_bf16 v[64:67], v[216:219], v[244:247], v[64:67]
	s_nop 1
	v_pk_mul_f32 v[84:85], v[84:85], v[228:229]
	v_pk_mul_f32 v[86:87], v[86:87], v[230:231]
	v_cvt_pk_bf16_f32 v88, v84, v85
	v_cvt_pk_bf16_f32 v90, v86, v87
	s_nop 1
	v_mov_b32_dpp v89, v88 quad_perm:[1,0,3,2] row_mask:0xf bank_mask:0xf
	v_mov_b32_dpp v91, v90 quad_perm:[1,0,3,2] row_mask:0xf bank_mask:0xf
	v_perm_b32 v88, v89, v88, v92
	v_perm_b32 v90, v91, v90, v92
	ds_write_b32 v93, v88 offset:13056
	ds_write_b32 v93, v90 offset:13600
	s_waitcnt lgkmcnt(0)
	s_barrier
	s_waitcnt lgkmcnt(0)
	s_cbranch_scc1 .LBB0_1021
